# GDN scan: full LDS drains in front of the masked U staging write removed in steps 1 and 2 (state-image write and U write now overlap)
# speedup vs baseline: 1.0064x; 1.0064x over previous
; DI bf16x8 tr2(const bf16_t* p0, const bf16_t* p1) { s16x4 a = trread(p0), b = trread(p1); return __builtin_shufflevector(a, b, 0, 1, 2, 3, 4, 5, 6, 7); }
; DI f32x4 mfma16(bf16x8 a, bf16x8 b, f32x4 c) { return __builtin_amdgcn_mfma_f32_16x16x32_bf16(a, b, c, 0, 0, 0); }
; DI void gdn_scan_item(const P& p, int item, unsigned char* smem) {
;     ...
;     auto storel = [&](const GdnRegs& R, int buf) {
;         const u32x4* rr = R.r;
;         bf16_t* sW = (bf16_t*)(smem + buf * BUFB); bf16_t* sQI = sW + 64 * 136; bf16_t* sKO = sQI + 64 * 136; bf16_t* sAT = sKO + 64 * 136; bf16_t* sU = sAT + 64 * 72;
; #pragma unroll
;         for (int k = 0; k < 2; ++k) {
;             const int e = tid + 512 * k, r = e >> 4, ch = e & 15; const int off = r * 136 + 8 * ch;
;             *(u32x4*)(sW + off) = rr[k]; *(u32x4*)(sQI + off) = rr[2 + k]; *(u32x4*)(sKO + off) = rr[4 + k];
;         }
;         { const int r = tid >> 3, ch = tid & 7; *(u32x4*)(sAT + r * 72 + 8 * ch) = rr[6]; }
;         if (tid < 256) { const int r = tid >> 2, ch = tid & 3; *(u32x4*)(sU + r * 40 + 8 * ch) = rr[7]; }
;     ...
; #pragma unroll
;             for (int k2 = 0; k2 < 2; ++k2) acc = mfma16(Bv[k2], ld8(sAT + (16 * mt + l15) * 72 + 32 * k2 + 8 * g), acc);
;             bf16_t* ob = OG + (size_t)prow(b, dir, 64 * c) * 512 + 128 * h + 32 * cq;
;             u32x2 ov; ov.x = pk2(acc[0], acc[1]); ov.y = pk2(acc[2], acc[3]);
;             *(u32x2*)(ob + sgn * ((16 * mt + l15) * 512) + 16 * nt + 4 * g) = ov;
;         }
; #pragma unroll
;         for (int j = 0; j < 2; ++j) {
;             const int dt = 2 * mt + j;
;             st[j] *= dec;
; #pragma unroll
;             for (int k2 = 0; k2 < 2; ++k2) {
;                 const bf16x8 ak = tr2(sKO + (32 * k2 + 8 * g + q4) * 136 + 16 * dt + 4 * p4, sKO + (32 * k2 + 8 * g + 4 + q4) * 136 + 16 * dt + 4 * p4);
;                 st[j] = mfma16(ak, Bv[k2], st[j]);
;             }
;         }
;         sBS[(nt * 4 + mt) * 64 + lane] = __builtin_bit_cast(u32x4, packacc(st[0], st[1]));
.LBB0_511:
	v_lshl_add_u32 v134, v125, 1, s28
	v_lshlrev_b32_e32 v197, 1, v157
	v_add3_u32 v187, v134, v185, v197
	ds_read_b64_tr_b16 v[226:227], v187 offset:35904
	ds_read_b64_tr_b16 v[224:225], v187 offset:34816
	ds_read_b64_tr_b16 v[230:231], v187 offset:44608
	ds_read_b64_tr_b16 v[234:235], v187 offset:35936
	ds_read_b64_tr_b16 v[232:233], v187 offset:34848
	ds_read_b64_tr_b16 v[238:239], v187 offset:44640
	v_add3_u32 v193, v134, v186, v197
	ds_read_b64_tr_b16 v[228:229], v193 offset:34816
	ds_read_b64_tr_b16 v[236:237], v193 offset:34848
	v_pk_mul_f32 v[98:99], v[98:99], v[132:133] op_sel_hi:[1,0]
	v_pk_mul_f32 v[96:97], v[96:97], v[132:133] op_sel_hi:[1,0]
	v_pk_mul_f32 v[102:103], v[102:103], v[132:133] op_sel_hi:[1,0]
	v_pk_mul_f32 v[100:101], v[100:101], v[132:133] op_sel_hi:[1,0]
	s_waitcnt lgkmcnt(6)
	v_mfma_f32_16x16x32_bf16 v[96:99], v[224:227], v[108:111], v[96:99]
	s_waitcnt vmcnt(9)
	ds_write_b128 v214, v[64:67] offset:34816
	s_ashr_i32 s41, s40, 31
	s_lshl_b64 s[4:5], s[40:41], 10
	s_waitcnt lgkmcnt(4)
	v_mfma_f32_16x16x32_bf16 v[100:103], v[232:235], v[108:111], v[100:103]
	s_waitcnt vmcnt(3)
	ds_write_b128 v215, v[72:75] offset:52224
	s_bitcmp1_b32 s27, 0
	v_lshl_add_u64 v[108:109], v[126:127], 0, s[4:5]
	s_cselect_b32 s4, 0x10400, 0
	s_waitcnt lgkmcnt(3)
	v_mfma_f32_16x16x32_bf16 v[96:99], v[228:231], v[104:107], v[96:99]
	s_add_i32 s27, s57, s4
	v_cvt_pk_bf16_f32 v112, v112, v113
	v_cvt_pk_bf16_f32 v113, v114, v115
	s_waitcnt lgkmcnt(2)
	v_mfma_f32_16x16x32_bf16 v[100:103], v[236:239], v[104:107], v[100:103]
	global_store_dwordx2 v[108:109], v[112:113], off
	s_nop 1
	v_cvt_pk_bf16_f32 v104, v96, v97
	v_cvt_pk_bf16_f32 v105, v98, v99
	s_nop 2
	v_cvt_pk_bf16_f32 v106, v100, v101
	v_cvt_pk_bf16_f32 v107, v102, v103
	ds_write_b128 v156, v[104:107]
	s_and_saveexec_b64 s[40:41], s[0:1]
	v_add3_u32 v216, s27, v161, v198
	ds_write_b128 v216, v[44:47] offset:61440
	s_or_b64 exec, exec, s[40:41]
	s_cmp_gt_u32 s26, 31
	v_readlane_b32 s12, v254, 56
	s_waitcnt lgkmcnt(0)
	s_barrier
	ds_read_b128 v[110:113], v117
	ds_read_b128 v[200:203], v117 offset:1024
	ds_read_b128 v[204:207], v117 offset:2048
	ds_read_b128 v[208:211], v117 offset:3072
	v_lshl_add_u32 v109, v121, 1, s27
	v_mov_b32_e32 v104, s21
	ds_read_b32 v108, v104 offset:4
	v_add_u32_e32 v132, v109, v162
	ds_read2_b64 v[224:227], v132 offset1:4
	ds_read2_b64 v[228:231], v132 offset0:8 offset1:12
	ds_read2_b64 v[236:239], v132 offset0:16 offset1:20
	ds_read2_b64 v[240:243], v132 offset0:24 offset1:28
	v_add_u32_e32 v109, v109, v158
	v_readlane_b32 s13, v254, 57
	s_cbranch_scc1 .LBB0_517
	v_add_co_u32_e32 v28, vcc, 0x13f5c000, v154
	s_nop 1
	v_addc_co_u32_e32 v29, vcc, 0, v155, vcc
	v_add_co_u32_e32 v32, vcc, 0x1515c000, v154
	s_nop 1
	v_addc_co_u32_e32 v33, vcc, 0, v155, vcc
	v_add_co_u32_e32 v40, vcc, 0x1635c000, v154
	global_load_dwordx4 v[28:31], v[28:29], off
	s_nop 0
	global_load_dwordx4 v[32:35], v[32:33], off
	v_addc_co_u32_e32 v41, vcc, 0, v155, vcc
	v_add_co_u32_e32 v48, vcc, 0x13f5c000, v152
	global_load_dwordx4 v[40:43], v[40:41], off
	s_nop 0
	v_addc_co_u32_e32 v49, vcc, 0, v153, vcc
	v_add_co_u32_e32 v52, vcc, 0x1515c000, v152
	s_nop 1
	v_addc_co_u32_e32 v53, vcc, 0, v153, vcc
	v_add_co_u32_e32 v64, vcc, 0x1635c000, v152
	global_load_dwordx4 v[48:51], v[48:49], off
	s_nop 0
	global_load_dwordx4 v[52:55], v[52:53], off
	v_addc_co_u32_e32 v65, vcc, 0, v153, vcc
	v_add_co_u32_e32 v72, vcc, 0x17554000, v150
	global_load_dwordx4 v[64:67], v[64:65], off
	s_nop 0
	v_addc_co_u32_e32 v73, vcc, 0, v151, vcc
	global_load_dwordx4 v[72:75], v[72:73], off
	s_and_saveexec_b64 s[40:41], s[0:1]
	s_cbranch_execz .LBB0_516
	v_lshl_add_u64 v[44:45], v[144:145], 0, s[44:45]
	v_add_co_u32_e32 v44, vcc, 0x12d5c000, v44
	s_nop 1
	v_addc_co_u32_e32 v45, vcc, 0, v45, vcc
	global_load_dwordx4 v[44:47], v[44:45], off nt

; DI void gdn_scan_item(const P& p, int item, unsigned char* smem) {
;     ...
;     auto storel = [&](const GdnRegs& R, int buf) {
;         const u32x4* rr = R.r;
;         bf16_t* sW = (bf16_t*)(smem + buf * BUFB); bf16_t* sQI = sW + 64 * 136; bf16_t* sKO = sQI + 64 * 136; bf16_t* sAT = sKO + 64 * 136; bf16_t* sU = sAT + 64 * 72;
; #pragma unroll
;         for (int k = 0; k < 2; ++k) {
;     ...
;         {
;             f32x4 acc = (f32x4){0.f, 0.f, 0.f, 0.f};
; #pragma unroll
;             for (int ks = 0; ks < 4; ++ks) { const bf16_t* r0 = sW + (16 * mt + l15) * 136 + 32 * ks + 4 * g; acc = mfma16(Bs[ks], ld4x2(r0, r0 + 16), acc); }
;             {
;                 const u32x2 uu = *(const u32x2*)(sU + (16 * mt + l15) * 40 + 16 * nt + 4 * g);
;                 u32x2 vv; vv.x = pk2(lo16(uu.x) - acc[0], hi16(uu.x) - acc[1]); vv.y = pk2(lo16(uu.y) - acc[2], hi16(uu.y) - acc[3]);
;                 *(u32x2*)(sVN + (16 * mt + l15) * 40 + 16 * nt + 4 * g) = vv;
;             }
;         }
;         __syncthreads();
;         bf16x8 Bv[2];
; #pragma unroll
;         for (int k2 = 0; k2 < 2; ++k2) Bv[k2] = tr2(sVN + (32 * k2 + 8 * g + q4) * 40 + 16 * nt + 4 * p4, sVN + (32 * k2 + 8 * g + 4 + q4) * 40 + 16 * nt + 4 * p4);
;         {
;             f32x4 acc = (f32x4){0.f, 0.f, 0.f, 0.f};
; #pragma unroll
;             for (int ks = 0; ks < 4; ++ks) { const bf16_t* r0 = sQI + (16 * mt + l15) * 136 + 32 * ks + 4 * g; acc = mfma16(Bs[ks], ld4x2(r0, r0 + 16), acc); }
; #pragma unroll
;             for (int k2 = 0; k2 < 2; ++k2) acc = mfma16(Bv[k2], ld8(sAT + (16 * mt + l15) * 72 + 32 * k2 + 8 * g), acc);
;             bf16_t* ob = OG + (size_t)prow(b, dir, 64 * c) * 512 + 128 * h + 32 * cq;
;             u32x2 ov; ov.x = pk2(acc[0], acc[1]); ov.y = pk2(acc[2], acc[3]);
;             *(u32x2*)(ob + sgn * ((16 * mt + l15) * 512) + 16 * nt + 4 * g) = ov;
;         }
; #pragma unroll
;         for (int j = 0; j < 2; ++j) {
;             const int dt = 2 * mt + j;
;             st[j] *= dec;
; #pragma unroll
;             for (int k2 = 0; k2 < 2; ++k2) {
;                 const bf16x8 ak = tr2(sKO + (32 * k2 + 8 * g + q4) * 136 + 16 * dt + 4 * p4, sKO + (32 * k2 + 8 * g + 4 + q4) * 136 + 16 * dt + 4 * p4);
;                 st[j] = mfma16(ak, Bv[k2], st[j]);
;             }
;         }
;         sBS[(nt * 4 + mt) * 64 + lane] = __builtin_bit_cast(u32x4, packacc(st[0], st[1]));
.LBB0_517:
	s_waitcnt lgkmcnt(3)
	v_mfma_f32_16x16x32_bf16 v[104:107], v[110:113], v[224:227], 0
	v_add3_u32 v114, v109, v163, v162
	ds_read_b64 v[232:233], v114 offset:61440
	v_add_u32_e32 v109, v109, v159
	s_waitcnt lgkmcnt(3)
	v_mfma_f32_16x16x32_bf16 v[104:107], v[200:203], v[228:231], v[104:107]
	v_add3_u32 v109, v109, v160, v199
	s_waitcnt lgkmcnt(0)
	v_lshlrev_b32_e32 v134, 16, v232
	v_mfma_f32_16x16x32_bf16 v[104:107], v[204:207], v[236:239], v[104:107]
	v_and_b32_e32 v114, 0xffff0000, v232
	s_sub_i32 s4, s22, 64
	v_mfma_f32_16x16x32_bf16 v[104:107], v[208:211], v[240:243], v[104:107]
	s_add_i32 s5, s22, 0xfffffec0
	s_cmp_lt_u32 s26, 3
	s_movk_i32 s6, 0x8ff
	s_nop 4
	v_sub_f32_e32 v104, v134, v104
	v_sub_f32_e32 v105, v114, v105
	v_cvt_pk_bf16_f32 v104, v104, v105
	v_lshlrev_b32_e32 v105, 16, v233
	v_sub_f32_e32 v105, v105, v106
	v_and_b32_e32 v106, 0xffff0000, v233
	v_sub_f32_e32 v106, v106, v107
	v_cvt_pk_bf16_f32 v105, v105, v106
	v_add_u32_e32 v114, 0x4000, v132
	ds_write_b64 v123, v[104:105]
	s_waitcnt lgkmcnt(0)
	s_barrier
	ds_read_b64_tr_b16 v[224:225], v164
	ds_read_b64_tr_b16 v[226:227], v165
	ds_read_b64_tr_b16 v[228:229], v183
	ds_read_b64_tr_b16 v[230:231], v184
	ds_read2_b64 v[232:235], v114 offset0:128 offset1:132
	ds_read2_b64 v[236:239], v114 offset0:136 offset1:140
	ds_read2_b64 v[240:243], v114 offset0:144 offset1:148
	ds_read2_b64 v[244:247], v114 offset0:152 offset1:156
	ds_read_b128 v[248:251], v109 offset:52224
	s_waitcnt lgkmcnt(4)
	v_mfma_f32_16x16x32_bf16 v[110:113], v[110:113], v[232:235], 0
	ds_read_b128 v[232:235], v109 offset:52288
	s_waitcnt vmcnt(8)
	ds_write_b128 v190, v[56:59]
	s_cselect_b32 s6, 0xff, s6
	s_cselect_b32 s7, s4, s5
	s_waitcnt lgkmcnt(5)
	v_mfma_f32_16x16x32_bf16 v[110:113], v[200:203], v[236:239], v[110:113]
	s_waitcnt vmcnt(7)
	ds_write_b128 v190, v[60:63] offset:17408
	s_cselect_b32 s8, s3, s2
	s_add_i32 s4, s6, s24
	s_waitcnt lgkmcnt(5)
	v_mfma_f32_16x16x32_bf16 v[110:113], v[204:207], v[240:243], v[110:113]
	s_waitcnt vmcnt(6)
	ds_write_b128 v190, v[68:71] offset:34816
	s_add_i32 s6, s4, 0xfffff741
	s_and_b64 s[4:5], s[38:39], exec
	s_waitcnt lgkmcnt(5)
	v_mfma_f32_16x16x32_bf16 v[110:113], v[208:211], v[244:247], v[110:113]
	s_waitcnt vmcnt(5)
	ds_write_b128 v192, v[76:79]
	s_cselect_b32 s4, s7, s6
	s_add_i32 s4, s4, s8
	s_waitcnt lgkmcnt(5)
	v_mfma_f32_16x16x32_bf16 v[110:113], v[224:227], v[248:251], v[110:113]
	s_waitcnt vmcnt(4)
	ds_write_b128 v192, v[80:83] offset:17408
	s_ashr_i32 s5, s4, 31
	s_lshl_b64 s[4:5], s[4:5], 10
	s_waitcnt lgkmcnt(5)
	v_mfma_f32_16x16x32_bf16 v[110:113], v[228:231], v[232:235], v[110:113]
	v_mul_f32_e64 v98, v98, v108
	v_mul_f32_e64 v99, v99, v108
	v_pk_mul_f32 v[96:97], v[96:97], v[108:109] op_sel_hi:[1,0]
	v_lshl_add_u32 v109, v125, 1, s27
	s_nop 3
	v_cvt_pk_bf16_f32 v110, v110, v111
	v_cvt_pk_bf16_f32 v111, v112, v113
	v_lshl_add_u64 v[112:113], v[126:127], 0, s[4:5]
	global_store_dwordx2 v[112:113], v[110:111], off
	v_add3_u32 v114, v109, v185, v197
	ds_read_b64_tr_b16 v[238:239], v114 offset:35904
	ds_read_b64_tr_b16 v[236:237], v114 offset:34816
	ds_read_b64_tr_b16 v[240:241], v114 offset:34848
	ds_read_b64_tr_b16 v[246:247], v114 offset:44608
	ds_read_b64_tr_b16 v[242:243], v114 offset:35936
	ds_read_b64_tr_b16 v[250:251], v114 offset:44640
	s_waitcnt lgkmcnt(4)
	v_mfma_f32_16x16x32_bf16 v[96:99], v[236:239], v[224:227], v[96:99]
	s_waitcnt vmcnt(3)
	ds_write_b128 v192, v[84:87] offset:34816
	v_add3_u32 v109, v109, v186, v197
	ds_read_b64_tr_b16 v[244:245], v109 offset:34816
	ds_read_b64_tr_b16 v[248:249], v109 offset:34848
	v_pk_mul_f32 v[102:103], v[102:103], v[108:109] op_sel_hi:[1,0]
	v_pk_mul_f32 v[100:101], v[100:101], v[108:109] op_sel_hi:[1,0]
	s_waitcnt lgkmcnt(1)
	v_mfma_f32_16x16x32_bf16 v[96:99], v[244:247], v[228:231], v[96:99]
	s_waitcnt vmcnt(2)
	ds_write_b128 v194, v[92:95] offset:52224
	v_mfma_f32_16x16x32_bf16 v[100:103], v[240:243], v[224:227], v[100:103]
	s_waitcnt lgkmcnt(1)
	v_mfma_f32_16x16x32_bf16 v[100:103], v[248:251], v[228:231], v[100:103]
	s_nop 3
	s_nop 0
	v_cvt_pk_bf16_f32 v104, v96, v97
	v_cvt_pk_bf16_f32 v105, v98, v99
	s_nop 1
	v_cvt_pk_bf16_f32 v106, v100, v101
	v_cvt_pk_bf16_f32 v107, v102, v103
	ds_write_b128 v156, v[104:107]
	s_and_saveexec_b64 s[40:41], s[0:1]
	ds_write_b128 v191, v[88:91] offset:61440
	s_or_b64 exec, exec, s[40:41]
	s_cmp_gt_u32 s26, 30
	s_waitcnt lgkmcnt(0)
	s_barrier
	ds_read_b128 v[112:115], v117
	ds_read_b128 v[248:251], v117 offset:1024
	ds_read_b128 v[198:201], v117 offset:2048
	ds_read_b128 v[202:205], v117 offset:3072
	ds_read2_b64 v[224:227], v188 offset1:4
	ds_read2_b64 v[228:231], v188 offset0:8 offset1:12
	ds_read2_b64 v[232:235], v188 offset0:16 offset1:20
	ds_read2_b64 v[236:239], v188 offset0:24 offset1:28
	ds_read_b64 v[240:241], v195 offset:61440
	v_mov_b32_e32 v104, s21
	ds_read_b32 v132, v104 offset:8
	s_cbranch_scc1 .LBB0_523
	v_add_co_u32_e32 v56, vcc, 0x13f60000, v154
	s_nop 1
	v_addc_co_u32_e32 v57, vcc, 0, v155, vcc
	v_add_co_u32_e32 v60, vcc, 0x15160000, v154
	s_nop 1
	v_addc_co_u32_e32 v61, vcc, 0, v155, vcc
	v_add_co_u32_e32 v68, vcc, 0x16360000, v154
	global_load_dwordx4 v[56:59], v[56:57], off
	s_nop 0
	global_load_dwordx4 v[60:63], v[60:61], off
	v_addc_co_u32_e32 v69, vcc, 0, v155, vcc
	v_add_co_u32_e32 v76, vcc, 0x13f60000, v152
	global_load_dwordx4 v[68:71], v[68:69], off
	s_nop 0
	v_addc_co_u32_e32 v77, vcc, 0, v153, vcc
	v_add_co_u32_e32 v80, vcc, 0x15160000, v152
	s_nop 1
	v_addc_co_u32_e32 v81, vcc, 0, v153, vcc
	v_add_co_u32_e32 v84, vcc, 0x16360000, v152
	global_load_dwordx4 v[76:79], v[76:77], off
	s_nop 0
	global_load_dwordx4 v[80:83], v[80:81], off
	v_addc_co_u32_e32 v85, vcc, 0, v153, vcc
	v_add_co_u32_e32 v92, vcc, 0x17556000, v150
	global_load_dwordx4 v[84:87], v[84:85], off
	s_nop 0
	v_addc_co_u32_e32 v93, vcc, 0, v151, vcc
	global_load_dwordx4 v[92:95], v[92:93], off
	s_and_saveexec_b64 s[40:41], s[0:1]
	s_cbranch_execz .LBB0_522
	v_lshl_add_u64 v[88:89], v[144:145], 0, s[44:45]
	v_add_co_u32_e32 v88, vcc, 0x12d60000, v88
	s_nop 1
	v_addc_co_u32_e32 v89, vcc, 0, v89, vcc
	global_load_dwordx4 v[88:91], v[88:89], off nt
